# sample-attention block rewritten by hand with f32-operand MFMA (16x16x4 f32), LDS-staged K/V/Q, 4 barriers per unit
# speedup vs baseline: 1.0354x; 1.0071x over previous
.LBB0_962:
	s_cmp_lt_u32 s30, 0x40001
	s_mov_b64 s[18:19], 0
	s_cselect_b64 s[26:27], -1, 0
	s_mov_b64 s[28:29], -1
	s_and_b64 vcc, exec, s[26:27]
	s_cbranch_vccz .LBB0_956
	s_branch .LBB0_961
.LT_entry:
	s_cmp_eq_u32 s64, 0
	s_cbranch_scc1 .LT_job0
	s_cmp_eq_u32 s64, 1
	s_cbranch_scc1 .LT_job1
	s_cmp_eq_u32 s64, 2
	s_cbranch_scc1 .LT_job2
	s_cmp_eq_u32 s64, 3
	s_cbranch_scc1 .LT_job3
	s_cmp_eq_u32 s64, 4
	s_cbranch_scc1 .LT_job4
	s_cmp_eq_u32 s64, 5
	s_cbranch_scc1 .LT_job5
	s_cmp_eq_u32 s64, 6
	s_cbranch_scc1 .LT_job6
	s_cmp_eq_u32 s64, 7
	s_cbranch_scc1 .LT_job7
	s_cmp_eq_u32 s64, 8
	s_cbranch_scc1 .LT_job8

.LT_done:
	s_cmp_eq_u32 s67, 0
	s_cbranch_scc1 .LT_ret0
	s_cmp_eq_u32 s67, 1
	s_cbranch_scc1 .LT_ret1
	s_cmp_eq_u32 s67, 2
	s_cbranch_scc1 .LT_ret2
	s_endpgm
.LBB0_963:
	s_or_b64 exec, exec, s[14:15]
	s_and_b64 s[14:15], s[16:17], exec

.LBB0_987:
	s_andn2_b64 vcc, exec, s[2:3]
	s_cbranch_vccnz .LBB0_1014
	v_and_b32_e32 v32, 63, v128
	v_and_b32_e32 v33, 15, v32
	v_lshrrev_b32_e32 v34, 4, v32
	v_readfirstlane_b32 s65, v128
	s_lshr_b32 s65, s65, 6
	v_lshrrev_b32_e32 v45, 4, v128
	v_and_b32_e32 v46, 15, v128
	v_lshlrev_b32_e32 v47, 4, v46
	v_lshl_add_u32 v35, v45, 10, v47
	s_movk_i32 s82, 0x110
	v_mul_u32_u24_e32 v36, s82, v45
	v_add_u32_e32 v36, v36, v47
	s_mul_i32 s83, s65, 0x5c00
	v_lshl_add_u32 v37, v32, 1, s83
	s_add_u32 s83, s65, 128
	s_mul_i32 s83, s83, 0x110
	v_lshl_add_u32 v38, v32, 2, s83
	v_add_u32_e32 v39, 0x880, v38
	v_and_b32_e32 v40, 7, v45
	s_movk_i32 s83, 0x5c00
	v_mul_u32_u24_e32 v40, s83, v40
	v_lshrrev_b32_e32 v47, 7, v128
	v_lshl_add_u32 v40, v47, 7, v40
	v_lshl_add_u32 v40, v46, 3, v40
	v_mul_u32_u24_e32 v41, s82, v33
	v_lshl_add_u32 v41, v34, 6, v41
	s_movk_i32 s83, 0x250
	v_mul_u32_u24_e32 v42, s83, v33
	s_movk_i32 s84, 0x90
	v_mul_u32_u24_e32 v47, s84, v34
	v_add_u32_e32 v42, v42, v47
	v_add_u32_e32 v42, 0x15400, v42
	s_movk_i32 s84, 0x2640
	v_mul_u32_u24_e32 v43, s84, v34
	v_lshl_add_u32 v43, v33, 2, v43
	v_add_u32_e32 v43, 0x9900, v43
	v_lshlrev_b32_e32 v44, 2, v32
	v_add_u32_e32 v44, 0x15400, v44
	v_and_b32_e32 v47, 1, v34
	v_lshlrev_b32_e32 v47, 2, v47
	v_sub_u32_e32 v90, v47, v33
	v_add_u32_e32 v90, 0x80, v90
	v_lshrrev_b32_e32 v89, 1, v34
	s_movk_i32 s84, 0x940
	v_mul_u32_u24_e32 v98, s84, v34
	v_lshl_add_u32 v98, v33, 2, v98
	v_add_u32_e32 v98, 0x15400, v98
	v_add_u32_e32 v206, 0x13200, v36
	v_mov_b32_e32 v97, 0xff800000
	v_mov_b32_e32 v86, 0
	v_xor_b32_e32 v47, 1, v32
	v_lshlrev_b32_e32 v200, 2, v47
	v_xor_b32_e32 v47, 2, v32
	v_lshlrev_b32_e32 v201, 2, v47
	v_xor_b32_e32 v47, 4, v32
	v_lshlrev_b32_e32 v202, 2, v47
	v_xor_b32_e32 v47, 8, v32
	v_lshlrev_b32_e32 v203, 2, v47
	v_xor_b32_e32 v47, 16, v32
	v_lshlrev_b32_e32 v204, 2, v47
	v_xor_b32_e32 v47, 32, v32
	v_lshlrev_b32_e32 v205, 2, v47
	v_lshlrev_b32_e32 v99, 4, v34
	v_add_u32_e32 v99, 0x19e00, v99
	v_and_b32_e32 v47, 1, v34
	v_lshlrev_b32_e32 v47, 13, v47
	v_lshl_add_u32 v47, v89, 7, v47
	v_lshl_add_u32 v91, v33, 1, v47
	s_add_u32 s68, s50, 0x14705000
	s_addc_u32 s69, s51, 0
	s_add_u32 s70, s50, 0x21605000
	s_addc_u32 s71, s51, 0
	v_readlane_b32 s72, v235, 9
	v_readlane_b32 s73, v235, 10
	s_mov_b32 s90, 0x3e000000
	s_mov_b32 s64, s34
.LSA_unit:
	s_and_b32 s66, s64, 3
	s_lshr_b32 s67, s64, 2
	s_lshl_b32 s82, s67, 17
	s_lshl_b32 s83, s66, 8
	s_add_u32 s82, s82, s83
	s_add_u32 s74, s20, s82
	s_addc_u32 s75, s21, 0
	s_add_u32 s76, s22, s82
	s_addc_u32 s77, s23, 0
	s_lshl_b32 s82, s67, 3
	s_add_u32 s82, s82, 0x2000
	s_mul_i32 s83, s82, 0x5c00
	s_add_u32 s78, s68, s83
	s_addc_u32 s79, s69, 0
	s_lshl_b32 s83, s66, 7
	s_add_u32 s84, s78, s83
	s_addc_u32 s85, s79, 0
	s_lshl_b32 s83, s66, 9
	s_add_u32 s86, s78, s83
	s_addc_u32 s87, s79, 0
	s_lshl_b32 s82, s82, 11
	s_add_u32 s82, s82, s83
	s_add_u32 s80, s70, s82
	s_addc_u32 s81, s71, 0
	global_load_dwordx4 v[48:51], v35, s[74:75] offset:0
	v_add_u32_e32 v93, 0x8000, v35
	v_add_u32_e32 v94, 0x10000, v35
	v_add_u32_e32 v95, 0x18000, v35
	global_load_dwordx4 v[52:55], v93, s[74:75]
	global_load_dwordx4 v[56:59], v94, s[74:75]
	global_load_dwordx4 v[60:63], v95, s[74:75]
	global_load_dwordx4 v[64:67], v35, s[76:77]
	global_load_dwordx4 v[68:71], v93, s[76:77]
	global_load_dwordx4 v[72:75], v94, s[76:77]
	global_load_dwordx4 v[76:79], v95, s[76:77]
	global_load_ushort v80, v37, s[84:85] offset:2048
	global_load_ushort v81, v37, s[84:85] offset:2560
	global_load_dwordx2 v[82:83], v40, s[86:87]
	s_lshl_b32 s82, s66, 2
	s_lshr_b32 s83, s65, 1
	s_add_u32 s82, s82, s83
	s_lshl_b32 s82, s82, 2
	v_mov_b32_e32 v47, s82
	global_load_dword v88, v47, s[72:73]
	ds_write_b32 v39, v86
	ds_write_b32 v39, v86 offset:39168
	s_waitcnt vmcnt(11)
	ds_write_b128 v36, v[48:51] offset:0
	s_waitcnt vmcnt(10)
	ds_write_b128 v36, v[52:55] offset:8704
	s_waitcnt vmcnt(9)
	ds_write_b128 v36, v[56:59] offset:17408
	s_waitcnt vmcnt(8)
	ds_write_b128 v36, v[60:63] offset:26112
	s_waitcnt vmcnt(7)
	ds_write_b128 v36, v[64:67] offset:39168
	s_waitcnt vmcnt(6)
	ds_write_b128 v36, v[68:71] offset:47872
	s_waitcnt vmcnt(5)
	ds_write_b128 v36, v[72:75] offset:56576
	s_waitcnt vmcnt(4)
	ds_write_b128 v36, v[76:79] offset:65280
	s_waitcnt vmcnt(1)
	v_lshlrev_b32_e32 v80, 16, v80
	v_lshlrev_b32_e32 v81, 16, v81
	ds_write_b32 v38, v80
	ds_write_b32 v38, v81 offset:39168
	v_lshlrev_b32_e32 v84, 16, v82
	v_and_b32_e32 v85, 0xffff0000, v82
	v_lshlrev_b32_e32 v86, 16, v83
	v_and_b32_e32 v87, 0xffff0000, v83
	ds_write_b128 v206, v[84:87]
	v_mov_b32_e32 v86, 0
	s_waitcnt lgkmcnt(0)
	s_barrier
	s_mov_b32 s82, s65
.LSA_tile:
	s_and_b32 s83, s82, 1
	s_lshr_b32 s84, s82, 1
	s_mul_i32 s85, s83, 0x1100
	s_add_u32 s85, s85, 0x13200
	v_add_u32_e32 v46, s85, v41
	s_mul_i32 s85, s84, 0x1100
	v_add_u32_e32 v47, s85, v41
	ds_read_b128 v[100:103], v46 offset:0
	ds_read_b128 v[104:107], v46 offset:16
	ds_read_b128 v[108:111], v46 offset:32
	ds_read_b128 v[112:115], v46 offset:48
	ds_read_b128 v[132:135], v47 offset:0
	ds_read_b128 v[136:139], v47 offset:16
	ds_read_b128 v[140:143], v47 offset:32
	ds_read_b128 v[144:147], v47 offset:48
	s_lshl_b32 s85, s66, 2
	s_lshl_b32 s86, s83, 1
	s_add_u32 s85, s85, s86
	s_add_u32 s85, s85, 1
	v_add_u32_e32 v93, s85, v89
	v_cvt_f32_u32_e32 v93, v93
	v_mul_f32_e32 v93, -0.5, v93
	v_exp_f32_e32 v93, v93
	s_mul_i32 s85, s83, 0x2500
	s_lshl_b32 s86, s84, 6
	s_add_u32 s85, s85, s86
	v_add_u32_e32 v95, s85, v98
	s_lshl_b32 s86, s84, 4
	v_subrev_u32_e32 v92, s86, v90
	s_waitcnt lgkmcnt(0)
	v_mfma_f32_16x16x4_f32 v[148:151], v100, v132, 0
	v_mfma_f32_16x16x4_f32 v[148:151], v101, v133, v[148:151]
	v_mfma_f32_16x16x4_f32 v[148:151], v102, v134, v[148:151]
	v_mfma_f32_16x16x4_f32 v[148:151], v103, v135, v[148:151]
	v_mfma_f32_16x16x4_f32 v[148:151], v104, v136, v[148:151]
	v_mfma_f32_16x16x4_f32 v[148:151], v105, v137, v[148:151]
	v_mfma_f32_16x16x4_f32 v[148:151], v106, v138, v[148:151]
	v_mfma_f32_16x16x4_f32 v[148:151], v107, v139, v[148:151]
	v_mfma_f32_16x16x4_f32 v[148:151], v108, v140, v[148:151]
	v_mfma_f32_16x16x4_f32 v[148:151], v109, v141, v[148:151]
	v_mfma_f32_16x16x4_f32 v[148:151], v110, v142, v[148:151]
	v_mfma_f32_16x16x4_f32 v[148:151], v111, v143, v[148:151]
	v_mfma_f32_16x16x4_f32 v[148:151], v112, v144, v[148:151]
	v_mfma_f32_16x16x4_f32 v[148:151], v113, v145, v[148:151]
	v_mfma_f32_16x16x4_f32 v[148:151], v114, v146, v[148:151]
	v_mfma_f32_16x16x4_f32 v[148:151], v115, v147, v[148:151]
	s_nop 9
	v_add_u32_e32 v94, 0, v92
	v_cvt_f32_i32_e32 v87, v94
	v_cmp_gt_u32_e32 vcc, 0x81, v94
	v_mul_f32_e32 v87, v93, v87
	v_fma_f32 v87, v148, s90, -v87
	v_cndmask_b32_e32 v87, v97, v87, vcc
	ds_write_b32 v95, v87 offset:0
	v_add_u32_e32 v94, 1, v92
	v_cvt_f32_i32_e32 v87, v94
	v_cmp_gt_u32_e32 vcc, 0x81, v94
	v_mul_f32_e32 v87, v93, v87
	v_fma_f32 v87, v149, s90, -v87
	v_cndmask_b32_e32 v87, v97, v87, vcc
	ds_write_b32 v95, v87 offset:592
	v_add_u32_e32 v94, 2, v92
	v_cvt_f32_i32_e32 v87, v94
	v_cmp_gt_u32_e32 vcc, 0x81, v94
	v_mul_f32_e32 v87, v93, v87
	v_fma_f32 v87, v150, s90, -v87
	v_cndmask_b32_e32 v87, v97, v87, vcc
	ds_write_b32 v95, v87 offset:1184
	v_add_u32_e32 v94, 3, v92
	v_cvt_f32_i32_e32 v87, v94
	v_cmp_gt_u32_e32 vcc, 0x81, v94
	v_mul_f32_e32 v87, v93, v87
	v_fma_f32 v87, v151, s90, -v87
	v_cndmask_b32_e32 v87, v97, v87, vcc
	ds_write_b32 v95, v87 offset:1776
	s_add_u32 s82, s82, 8
	s_cmp_lt_u32 s82, 18
	s_cbranch_scc1 .LSA_tile
	s_waitcnt lgkmcnt(0)
	s_barrier
	s_waitcnt vmcnt(0)
	s_lshl_b32 s82, s65, 2
	s_add_u32 s82, s82, 0
	s_mul_i32 s83, s82, 0x250
	v_add_u32_e32 v87, s83, v44
	v_cmp_gt_u32_e32 vcc, 16, v32
	ds_read_b32 v60, v87
	ds_read_b32 v61, v87 offset:256
	ds_read_b32 v62, v87 offset:512
	s_waitcnt lgkmcnt(0)
	v_cndmask_b32_e32 v62, v97, v62, vcc
	v_max3_f32 v63, v60, v61, v62
	v_max_f32_e32 v63, v63, v88
	ds_bpermute_b32 v64, v200, v63
	s_waitcnt lgkmcnt(0)
	v_max_f32_e32 v63, v63, v64
	ds_bpermute_b32 v64, v201, v63
	s_waitcnt lgkmcnt(0)
	v_max_f32_e32 v63, v63, v64
	ds_bpermute_b32 v64, v202, v63
	s_waitcnt lgkmcnt(0)
	v_max_f32_e32 v63, v63, v64
	ds_bpermute_b32 v64, v203, v63
	s_waitcnt lgkmcnt(0)
	v_max_f32_e32 v63, v63, v64
	ds_bpermute_b32 v64, v204, v63
	s_waitcnt lgkmcnt(0)
	v_max_f32_e32 v63, v63, v64
	ds_bpermute_b32 v64, v205, v63
	s_waitcnt lgkmcnt(0)
	v_max_f32_e32 v63, v63, v64
	v_sub_f32_e32 v60, v60, v63
	v_mul_f32_e32 v60, 0x3fb8aa3b, v60
	v_exp_f32_e32 v60, v60
	v_sub_f32_e32 v61, v61, v63
	v_mul_f32_e32 v61, 0x3fb8aa3b, v61
	v_exp_f32_e32 v61, v61
	v_sub_f32_e32 v62, v62, v63
	v_mul_f32_e32 v62, 0x3fb8aa3b, v62
	v_exp_f32_e32 v62, v62
	v_sub_f32_e32 v65, v88, v63
	v_mul_f32_e32 v65, 0x3fb8aa3b, v65
	v_exp_f32_e32 v65, v65
	ds_write_b32 v87, v60
	ds_write_b32 v87, v61 offset:256
	s_and_saveexec_b64 s[88:89], vcc
	ds_write_b32 v87, v62 offset:512
	s_mov_b64 exec, s[88:89]
	v_add_f32_e32 v66, v60, v61
	v_add_f32_e32 v66, v66, v62
	ds_bpermute_b32 v64, v200, v66
	s_waitcnt lgkmcnt(0)
	v_add_f32_e32 v66, v66, v64
	ds_bpermute_b32 v64, v201, v66
	s_waitcnt lgkmcnt(0)
	v_add_f32_e32 v66, v66, v64
	ds_bpermute_b32 v64, v202, v66
	s_waitcnt lgkmcnt(0)
	v_add_f32_e32 v66, v66, v64
	ds_bpermute_b32 v64, v203, v66
	s_waitcnt lgkmcnt(0)
	v_add_f32_e32 v66, v66, v64
	ds_bpermute_b32 v64, v204, v66
	s_waitcnt lgkmcnt(0)
	v_add_f32_e32 v66, v66, v64
	ds_bpermute_b32 v64, v205, v66
	s_waitcnt lgkmcnt(0)
	v_add_f32_e32 v66, v66, v64
	v_add_f32_e32 v66, v66, v65
	v_rcp_f32_e32 v66, v66
	s_nop 0
	s_lshl_b32 s83, s82, 2
	s_add_u32 s83, s83, 0x19e00
	v_mov_b32_e32 v67, s83
	ds_write_b32 v67, v66
	s_lshl_b32 s82, s65, 2
	s_add_u32 s82, s82, 1
	s_mul_i32 s83, s82, 0x250
	v_add_u32_e32 v87, s83, v44
	v_cmp_gt_u32_e32 vcc, 16, v32
	ds_read_b32 v60, v87
	ds_read_b32 v61, v87 offset:256
	ds_read_b32 v62, v87 offset:512
	s_waitcnt lgkmcnt(0)
	v_cndmask_b32_e32 v62, v97, v62, vcc
	v_max3_f32 v63, v60, v61, v62
	v_max_f32_e32 v63, v63, v88
	ds_bpermute_b32 v64, v200, v63
	s_waitcnt lgkmcnt(0)
	v_max_f32_e32 v63, v63, v64
	ds_bpermute_b32 v64, v201, v63
	s_waitcnt lgkmcnt(0)
	v_max_f32_e32 v63, v63, v64
	ds_bpermute_b32 v64, v202, v63
	s_waitcnt lgkmcnt(0)
	v_max_f32_e32 v63, v63, v64
	ds_bpermute_b32 v64, v203, v63
	s_waitcnt lgkmcnt(0)
	v_max_f32_e32 v63, v63, v64
	ds_bpermute_b32 v64, v204, v63
	s_waitcnt lgkmcnt(0)
	v_max_f32_e32 v63, v63, v64
	ds_bpermute_b32 v64, v205, v63
	s_waitcnt lgkmcnt(0)
	v_max_f32_e32 v63, v63, v64
	v_sub_f32_e32 v60, v60, v63
	v_mul_f32_e32 v60, 0x3fb8aa3b, v60
	v_exp_f32_e32 v60, v60
	v_sub_f32_e32 v61, v61, v63
	v_mul_f32_e32 v61, 0x3fb8aa3b, v61
	v_exp_f32_e32 v61, v61
	v_sub_f32_e32 v62, v62, v63
	v_mul_f32_e32 v62, 0x3fb8aa3b, v62
	v_exp_f32_e32 v62, v62
	v_sub_f32_e32 v65, v88, v63
	v_mul_f32_e32 v65, 0x3fb8aa3b, v65
	v_exp_f32_e32 v65, v65
	ds_write_b32 v87, v60
	ds_write_b32 v87, v61 offset:256
	s_and_saveexec_b64 s[88:89], vcc
	ds_write_b32 v87, v62 offset:512
	s_mov_b64 exec, s[88:89]
	v_add_f32_e32 v66, v60, v61
	v_add_f32_e32 v66, v66, v62
	ds_bpermute_b32 v64, v200, v66
	s_waitcnt lgkmcnt(0)
	v_add_f32_e32 v66, v66, v64
	ds_bpermute_b32 v64, v201, v66
	s_waitcnt lgkmcnt(0)
	v_add_f32_e32 v66, v66, v64
	ds_bpermute_b32 v64, v202, v66
	s_waitcnt lgkmcnt(0)
	v_add_f32_e32 v66, v66, v64
	ds_bpermute_b32 v64, v203, v66
	s_waitcnt lgkmcnt(0)
	v_add_f32_e32 v66, v66, v64
	ds_bpermute_b32 v64, v204, v66
	s_waitcnt lgkmcnt(0)
	v_add_f32_e32 v66, v66, v64
	ds_bpermute_b32 v64, v205, v66
	s_waitcnt lgkmcnt(0)
	v_add_f32_e32 v66, v66, v64
	v_add_f32_e32 v66, v66, v65
	v_rcp_f32_e32 v66, v66
	s_nop 0
	s_lshl_b32 s83, s82, 2
	s_add_u32 s83, s83, 0x19e00
	v_mov_b32_e32 v67, s83
	ds_write_b32 v67, v66
	s_lshl_b32 s82, s65, 2
	s_add_u32 s82, s82, 2
	s_mul_i32 s83, s82, 0x250
	v_add_u32_e32 v87, s83, v44
	v_cmp_gt_u32_e32 vcc, 16, v32
	ds_read_b32 v60, v87
	ds_read_b32 v61, v87 offset:256
	ds_read_b32 v62, v87 offset:512
	s_waitcnt lgkmcnt(0)
	v_cndmask_b32_e32 v62, v97, v62, vcc
	v_max3_f32 v63, v60, v61, v62
	v_max_f32_e32 v63, v63, v88
	ds_bpermute_b32 v64, v200, v63
	s_waitcnt lgkmcnt(0)
	v_max_f32_e32 v63, v63, v64
	ds_bpermute_b32 v64, v201, v63
	s_waitcnt lgkmcnt(0)
	v_max_f32_e32 v63, v63, v64
	ds_bpermute_b32 v64, v202, v63
	s_waitcnt lgkmcnt(0)
	v_max_f32_e32 v63, v63, v64
	ds_bpermute_b32 v64, v203, v63
	s_waitcnt lgkmcnt(0)
	v_max_f32_e32 v63, v63, v64
	ds_bpermute_b32 v64, v204, v63
	s_waitcnt lgkmcnt(0)
	v_max_f32_e32 v63, v63, v64
	ds_bpermute_b32 v64, v205, v63
	s_waitcnt lgkmcnt(0)
	v_max_f32_e32 v63, v63, v64
	v_sub_f32_e32 v60, v60, v63
	v_mul_f32_e32 v60, 0x3fb8aa3b, v60
	v_exp_f32_e32 v60, v60
	v_sub_f32_e32 v61, v61, v63
	v_mul_f32_e32 v61, 0x3fb8aa3b, v61
	v_exp_f32_e32 v61, v61
	v_sub_f32_e32 v62, v62, v63
	v_mul_f32_e32 v62, 0x3fb8aa3b, v62
	v_exp_f32_e32 v62, v62
	v_sub_f32_e32 v65, v88, v63
	v_mul_f32_e32 v65, 0x3fb8aa3b, v65
	v_exp_f32_e32 v65, v65
	ds_write_b32 v87, v60
	ds_write_b32 v87, v61 offset:256
	s_and_saveexec_b64 s[88:89], vcc
	ds_write_b32 v87, v62 offset:512
	s_mov_b64 exec, s[88:89]
	v_add_f32_e32 v66, v60, v61
	v_add_f32_e32 v66, v66, v62
	ds_bpermute_b32 v64, v200, v66
	s_waitcnt lgkmcnt(0)
	v_add_f32_e32 v66, v66, v64
	ds_bpermute_b32 v64, v201, v66
	s_waitcnt lgkmcnt(0)
	v_add_f32_e32 v66, v66, v64
	ds_bpermute_b32 v64, v202, v66
	s_waitcnt lgkmcnt(0)
	v_add_f32_e32 v66, v66, v64
	ds_bpermute_b32 v64, v203, v66
	s_waitcnt lgkmcnt(0)
	v_add_f32_e32 v66, v66, v64
	ds_bpermute_b32 v64, v204, v66
	s_waitcnt lgkmcnt(0)
	v_add_f32_e32 v66, v66, v64
	ds_bpermute_b32 v64, v205, v66
	s_waitcnt lgkmcnt(0)
	v_add_f32_e32 v66, v66, v64
	v_add_f32_e32 v66, v66, v65
	v_rcp_f32_e32 v66, v66
	s_nop 0
	s_lshl_b32 s83, s82, 2
	s_add_u32 s83, s83, 0x19e00
	v_mov_b32_e32 v67, s83
	ds_write_b32 v67, v66
	s_lshl_b32 s82, s65, 2
	s_add_u32 s82, s82, 3
	s_mul_i32 s83, s82, 0x250
	v_add_u32_e32 v87, s83, v44
	v_cmp_gt_u32_e32 vcc, 16, v32
	ds_read_b32 v60, v87
	ds_read_b32 v61, v87 offset:256
	ds_read_b32 v62, v87 offset:512
	s_waitcnt lgkmcnt(0)
	v_cndmask_b32_e32 v62, v97, v62, vcc
	v_max3_f32 v63, v60, v61, v62
	v_max_f32_e32 v63, v63, v88
	ds_bpermute_b32 v64, v200, v63
	s_waitcnt lgkmcnt(0)
	v_max_f32_e32 v63, v63, v64
	ds_bpermute_b32 v64, v201, v63
	s_waitcnt lgkmcnt(0)
	v_max_f32_e32 v63, v63, v64
	ds_bpermute_b32 v64, v202, v63
	s_waitcnt lgkmcnt(0)
	v_max_f32_e32 v63, v63, v64
	ds_bpermute_b32 v64, v203, v63
	s_waitcnt lgkmcnt(0)
	v_max_f32_e32 v63, v63, v64
	ds_bpermute_b32 v64, v204, v63
	s_waitcnt lgkmcnt(0)
	v_max_f32_e32 v63, v63, v64
	ds_bpermute_b32 v64, v205, v63
	s_waitcnt lgkmcnt(0)
	v_max_f32_e32 v63, v63, v64
	v_sub_f32_e32 v60, v60, v63
	v_mul_f32_e32 v60, 0x3fb8aa3b, v60
	v_exp_f32_e32 v60, v60
	v_sub_f32_e32 v61, v61, v63
	v_mul_f32_e32 v61, 0x3fb8aa3b, v61
	v_exp_f32_e32 v61, v61
	v_sub_f32_e32 v62, v62, v63
	v_mul_f32_e32 v62, 0x3fb8aa3b, v62
	v_exp_f32_e32 v62, v62
	v_sub_f32_e32 v65, v88, v63
	v_mul_f32_e32 v65, 0x3fb8aa3b, v65
	v_exp_f32_e32 v65, v65
	ds_write_b32 v87, v60
	ds_write_b32 v87, v61 offset:256
	s_and_saveexec_b64 s[88:89], vcc
	ds_write_b32 v87, v62 offset:512
	s_mov_b64 exec, s[88:89]
	v_add_f32_e32 v66, v60, v61
	v_add_f32_e32 v66, v66, v62
	ds_bpermute_b32 v64, v200, v66
	s_waitcnt lgkmcnt(0)
	v_add_f32_e32 v66, v66, v64
	ds_bpermute_b32 v64, v201, v66
	s_waitcnt lgkmcnt(0)
	v_add_f32_e32 v66, v66, v64
	ds_bpermute_b32 v64, v202, v66
	s_waitcnt lgkmcnt(0)
	v_add_f32_e32 v66, v66, v64
	ds_bpermute_b32 v64, v203, v66
	s_waitcnt lgkmcnt(0)
	v_add_f32_e32 v66, v66, v64
	ds_bpermute_b32 v64, v204, v66
	s_waitcnt lgkmcnt(0)
	v_add_f32_e32 v66, v66, v64
	ds_bpermute_b32 v64, v205, v66
	s_waitcnt lgkmcnt(0)
	v_add_f32_e32 v66, v66, v64
	v_add_f32_e32 v66, v66, v65
	v_rcp_f32_e32 v66, v66
	s_nop 0
	s_lshl_b32 s83, s82, 2
	s_add_u32 s83, s83, 0x19e00
	v_mov_b32_e32 v67, s83
	ds_write_b32 v67, v66
	s_waitcnt lgkmcnt(0)
	s_barrier
	s_and_b32 s83, s65, 1
	s_lshr_b32 s84, s65, 1
	s_mul_i32 s85, s83, 0x2500
	v_add_u32_e32 v46, s85, v42
	s_lshl_b32 s85, s84, 6
	v_add_u32_e32 v47, s85, v43
	ds_read_b128 v[48:51], v46 offset:0
	ds_read_b128 v[52:55], v46 offset:16
	ds_read_b128 v[56:59], v46 offset:32
	ds_read_b128 v[60:63], v46 offset:48
	ds_read_b128 v[64:67], v46 offset:64
	ds_read_b128 v[68:71], v46 offset:80
	ds_read_b128 v[72:75], v46 offset:96
	ds_read_b128 v[76:79], v46 offset:112
	ds_read_b128 v[80:83], v46 offset:128
	ds_read_b32 v152, v47 offset:0
	ds_read_b32 v153, v47 offset:272
	ds_read_b32 v154, v47 offset:544
	ds_read_b32 v155, v47 offset:816
	ds_read_b32 v156, v47 offset:1088
	ds_read_b32 v157, v47 offset:1360
	ds_read_b32 v158, v47 offset:1632
	ds_read_b32 v159, v47 offset:1904
	ds_read_b32 v160, v47 offset:2176
	ds_read_b32 v161, v47 offset:2448
	ds_read_b32 v162, v47 offset:2720
	ds_read_b32 v163, v47 offset:2992
	ds_read_b32 v164, v47 offset:3264
	ds_read_b32 v165, v47 offset:3536
	ds_read_b32 v166, v47 offset:3808
	ds_read_b32 v167, v47 offset:4080
	ds_read_b32 v168, v47 offset:4352
	ds_read_b32 v169, v47 offset:4624
	ds_read_b32 v170, v47 offset:4896
	ds_read_b32 v171, v47 offset:5168
	ds_read_b32 v172, v47 offset:5440
	ds_read_b32 v173, v47 offset:5712
	ds_read_b32 v174, v47 offset:5984
	ds_read_b32 v175, v47 offset:6256
	ds_read_b32 v176, v47 offset:6528
	ds_read_b32 v177, v47 offset:6800
	ds_read_b32 v178, v47 offset:7072
	ds_read_b32 v179, v47 offset:7344
	ds_read_b32 v180, v47 offset:7616
	ds_read_b32 v181, v47 offset:7888
	ds_read_b32 v182, v47 offset:8160
	ds_read_b32 v183, v47 offset:8432
	ds_read_b32 v184, v47 offset:8704
	ds_read_b32 v185, v47 offset:8976
	ds_read_b32 v186, v47 offset:9248
	ds_read_b32 v187, v47 offset:9520
	s_lshl_b32 s85, s83, 6
	v_add_u32_e32 v94, s85, v99
	ds_read_b32 v208, v94 offset:0
	ds_read_b32 v209, v94 offset:4
	ds_read_b32 v210, v94 offset:8
	ds_read_b32 v211, v94 offset:12
	s_waitcnt lgkmcnt(0)
	v_mfma_f32_16x16x4_f32 v[148:151], v48, v152, 0
	v_mfma_f32_16x16x4_f32 v[148:151], v49, v153, v[148:151]
	v_mfma_f32_16x16x4_f32 v[148:151], v50, v154, v[148:151]
	v_mfma_f32_16x16x4_f32 v[148:151], v51, v155, v[148:151]
	v_mfma_f32_16x16x4_f32 v[148:151], v52, v156, v[148:151]
	v_mfma_f32_16x16x4_f32 v[148:151], v53, v157, v[148:151]
	v_mfma_f32_16x16x4_f32 v[148:151], v54, v158, v[148:151]
	v_mfma_f32_16x16x4_f32 v[148:151], v55, v159, v[148:151]
	v_mfma_f32_16x16x4_f32 v[148:151], v56, v160, v[148:151]
	v_mfma_f32_16x16x4_f32 v[148:151], v57, v161, v[148:151]
	v_mfma_f32_16x16x4_f32 v[148:151], v58, v162, v[148:151]
	v_mfma_f32_16x16x4_f32 v[148:151], v59, v163, v[148:151]
	v_mfma_f32_16x16x4_f32 v[148:151], v60, v164, v[148:151]
	v_mfma_f32_16x16x4_f32 v[148:151], v61, v165, v[148:151]
	v_mfma_f32_16x16x4_f32 v[148:151], v62, v166, v[148:151]
	v_mfma_f32_16x16x4_f32 v[148:151], v63, v167, v[148:151]
	v_mfma_f32_16x16x4_f32 v[148:151], v64, v168, v[148:151]
	v_mfma_f32_16x16x4_f32 v[148:151], v65, v169, v[148:151]
	v_mfma_f32_16x16x4_f32 v[148:151], v66, v170, v[148:151]
	v_mfma_f32_16x16x4_f32 v[148:151], v67, v171, v[148:151]
	v_mfma_f32_16x16x4_f32 v[148:151], v68, v172, v[148:151]
	v_mfma_f32_16x16x4_f32 v[148:151], v69, v173, v[148:151]
	v_mfma_f32_16x16x4_f32 v[148:151], v70, v174, v[148:151]
	v_mfma_f32_16x16x4_f32 v[148:151], v71, v175, v[148:151]
	v_mfma_f32_16x16x4_f32 v[148:151], v72, v176, v[148:151]
	v_mfma_f32_16x16x4_f32 v[148:151], v73, v177, v[148:151]
	v_mfma_f32_16x16x4_f32 v[148:151], v74, v178, v[148:151]
	v_mfma_f32_16x16x4_f32 v[148:151], v75, v179, v[148:151]
	v_mfma_f32_16x16x4_f32 v[148:151], v76, v180, v[148:151]
	v_mfma_f32_16x16x4_f32 v[148:151], v77, v181, v[148:151]
	v_mfma_f32_16x16x4_f32 v[148:151], v78, v182, v[148:151]
	v_mfma_f32_16x16x4_f32 v[148:151], v79, v183, v[148:151]
	v_mfma_f32_16x16x4_f32 v[148:151], v80, v184, v[148:151]
	v_mfma_f32_16x16x4_f32 v[148:151], v81, v185, v[148:151]
	v_mfma_f32_16x16x4_f32 v[148:151], v82, v186, v[148:151]
	v_mfma_f32_16x16x4_f32 v[148:151], v83, v187, v[148:151]
	s_lshl_b32 s85, s83, 8
	s_lshl_b32 s86, s84, 5
	s_add_u32 s85, s85, s86
	v_add_u32_e32 v95, s85, v91
	s_nop 6
	v_add_u32_e32 v207, 0x1000, v95
	v_mul_f32_e32 v64, v148, v208
	v_cvt_pk_bf16_f32 v64, v64, v86
	global_store_short v95, v64, s[80:81] offset:0
	v_mul_f32_e32 v65, v149, v209
	v_cvt_pk_bf16_f32 v65, v65, v86
	global_store_short v95, v65, s[80:81] offset:2048
	v_mul_f32_e32 v66, v150, v210
	v_cvt_pk_bf16_f32 v66, v66, v86
	global_store_short v207, v66, s[80:81] offset:0
	v_mul_f32_e32 v67, v151, v211
	v_cvt_pk_bf16_f32 v67, v67, v86
	global_store_short v207, v67, s[80:81] offset:2048
	s_barrier
	s_add_u32 s64, s64, s94
	s_cmp_lt_u32 s64, 0x200
	s_cbranch_scc1 .LSA_unit
